# prologue adaLN: silu table with 10 loads in flight, GEMV loop 2-deep software pipeline (16 row loads in flight per wave)
# speedup vs baseline: 1.0827x; 1.0827x over previous
.LBB0_8:
	s_and_b64 vcc, exec, s[48:49]
	s_cbranch_vccnz .LBB0_13
	s_and_saveexec_b64 s[48:49], s[6:7]
	s_cbranch_execz .LBB0_12
	v_mov_b64_e32 v[2:3], v[28:29]
	s_mov_b64 vcc, 0x1000
	global_load_dword v40, v[2:3], off
	global_load_dword v41, v[2:3], off offset:2048
	v_lshl_add_u64 v[2:3], v[2:3], 0, vcc
	global_load_dword v42, v[2:3], off
	global_load_dword v43, v[2:3], off offset:2048
	v_lshl_add_u64 v[2:3], v[2:3], 0, vcc
	global_load_dword v44, v[2:3], off
	global_load_dword v45, v[2:3], off offset:2048
	v_lshl_add_u64 v[2:3], v[2:3], 0, vcc
	global_load_dword v46, v[2:3], off
	global_load_dword v47, v[2:3], off offset:2048
	v_mov_b32_e32 v24, v22
	v_lshl_add_u64 v[6:7], v[24:25], 2, s[28:29]
	global_load_dword v48, v[6:7], off
	global_load_dword v49, v[6:7], off offset:2048
	s_waitcnt vmcnt(9)
	v_mul_f32_e32 v6, 0xbfb8aa3b, v40
	v_exp_f32_e32 v6, v6
	s_nop 0
	v_add_f32_e32 v6, 1.0, v6
	v_div_scale_f32 v7, s[52:53], v6, v6, v40
	v_rcp_f32_e32 v8, v7
	v_div_scale_f32 v9, vcc, v40, v6, v40
	v_fma_f32 v10, -v7, v8, 1.0
	v_fmac_f32_e32 v8, v10, v8
	v_mul_f32_e32 v10, v9, v8
	v_fma_f32 v11, -v7, v10, v9
	v_fmac_f32_e32 v10, v11, v8
	v_fma_f32 v7, -v7, v10, v9
	v_div_fmas_f32 v7, v7, v8, v10
	v_div_fixup_f32 v5, v7, v6, v40
	ds_write_b32 v39, v5
	s_waitcnt vmcnt(8)
	v_mul_f32_e32 v6, 0xbfb8aa3b, v41
	v_exp_f32_e32 v6, v6
	s_nop 0
	v_add_f32_e32 v6, 1.0, v6
	v_div_scale_f32 v7, s[52:53], v6, v6, v41
	v_rcp_f32_e32 v8, v7
	v_div_scale_f32 v9, vcc, v41, v6, v41
	v_fma_f32 v10, -v7, v8, 1.0
	v_fmac_f32_e32 v8, v10, v8
	v_mul_f32_e32 v10, v9, v8
	v_fma_f32 v11, -v7, v10, v9
	v_fmac_f32_e32 v10, v11, v8
	v_fma_f32 v7, -v7, v10, v9
	v_div_fmas_f32 v7, v7, v8, v10
	v_div_fixup_f32 v5, v7, v6, v41
	ds_write_b32 v39, v5 offset:2048
	s_waitcnt vmcnt(7)
	v_mul_f32_e32 v6, 0xbfb8aa3b, v42
	v_exp_f32_e32 v6, v6
	s_nop 0
	v_add_f32_e32 v6, 1.0, v6
	v_div_scale_f32 v7, s[52:53], v6, v6, v42
	v_rcp_f32_e32 v8, v7
	v_div_scale_f32 v9, vcc, v42, v6, v42
	v_fma_f32 v10, -v7, v8, 1.0
	v_fmac_f32_e32 v8, v10, v8
	v_mul_f32_e32 v10, v9, v8
	v_fma_f32 v11, -v7, v10, v9
	v_fmac_f32_e32 v10, v11, v8
	v_fma_f32 v7, -v7, v10, v9
	v_div_fmas_f32 v7, v7, v8, v10
	v_div_fixup_f32 v5, v7, v6, v42
	ds_write_b32 v39, v5 offset:4096
	s_waitcnt vmcnt(6)
	v_mul_f32_e32 v6, 0xbfb8aa3b, v43
	v_exp_f32_e32 v6, v6
	s_nop 0
	v_add_f32_e32 v6, 1.0, v6
	v_div_scale_f32 v7, s[52:53], v6, v6, v43
	v_rcp_f32_e32 v8, v7
	v_div_scale_f32 v9, vcc, v43, v6, v43
	v_fma_f32 v10, -v7, v8, 1.0
	v_fmac_f32_e32 v8, v10, v8
	v_mul_f32_e32 v10, v9, v8
	v_fma_f32 v11, -v7, v10, v9
	v_fmac_f32_e32 v10, v11, v8
	v_fma_f32 v7, -v7, v10, v9
	v_div_fmas_f32 v7, v7, v8, v10
	v_div_fixup_f32 v5, v7, v6, v43
	ds_write_b32 v39, v5 offset:6144
	s_waitcnt vmcnt(5)
	v_mul_f32_e32 v6, 0xbfb8aa3b, v44
	v_exp_f32_e32 v6, v6
	s_nop 0
	v_add_f32_e32 v6, 1.0, v6
	v_div_scale_f32 v7, s[52:53], v6, v6, v44
	v_rcp_f32_e32 v8, v7
	v_div_scale_f32 v9, vcc, v44, v6, v44
	v_fma_f32 v10, -v7, v8, 1.0
	v_fmac_f32_e32 v8, v10, v8
	v_mul_f32_e32 v10, v9, v8
	v_fma_f32 v11, -v7, v10, v9
	v_fmac_f32_e32 v10, v11, v8
	v_fma_f32 v7, -v7, v10, v9
	v_div_fmas_f32 v7, v7, v8, v10
	v_div_fixup_f32 v5, v7, v6, v44
	ds_write_b32 v39, v5 offset:8192
	s_waitcnt vmcnt(4)
	v_mul_f32_e32 v6, 0xbfb8aa3b, v45
	v_exp_f32_e32 v6, v6
	s_nop 0
	v_add_f32_e32 v6, 1.0, v6
	v_div_scale_f32 v7, s[52:53], v6, v6, v45
	v_rcp_f32_e32 v8, v7
	v_div_scale_f32 v9, vcc, v45, v6, v45
	v_fma_f32 v10, -v7, v8, 1.0
	v_fmac_f32_e32 v8, v10, v8
	v_mul_f32_e32 v10, v9, v8
	v_fma_f32 v11, -v7, v10, v9
	v_fmac_f32_e32 v10, v11, v8
	v_fma_f32 v7, -v7, v10, v9
	v_div_fmas_f32 v7, v7, v8, v10
	v_div_fixup_f32 v5, v7, v6, v45
	ds_write_b32 v39, v5 offset:10240
	s_waitcnt vmcnt(3)
	v_mul_f32_e32 v6, 0xbfb8aa3b, v46
	v_exp_f32_e32 v6, v6
	s_nop 0
	v_add_f32_e32 v6, 1.0, v6
	v_div_scale_f32 v7, s[52:53], v6, v6, v46
	v_rcp_f32_e32 v8, v7
	v_div_scale_f32 v9, vcc, v46, v6, v46
	v_fma_f32 v10, -v7, v8, 1.0
	v_fmac_f32_e32 v8, v10, v8
	v_mul_f32_e32 v10, v9, v8
	v_fma_f32 v11, -v7, v10, v9
	v_fmac_f32_e32 v10, v11, v8
	v_fma_f32 v7, -v7, v10, v9
	v_div_fmas_f32 v7, v7, v8, v10
	v_div_fixup_f32 v5, v7, v6, v46
	ds_write_b32 v39, v5 offset:12288
	s_waitcnt vmcnt(2)
	v_mul_f32_e32 v6, 0xbfb8aa3b, v47
	v_exp_f32_e32 v6, v6
	s_nop 0
	v_add_f32_e32 v6, 1.0, v6
	v_div_scale_f32 v7, s[52:53], v6, v6, v47
	v_rcp_f32_e32 v8, v7
	v_div_scale_f32 v9, vcc, v47, v6, v47
	v_fma_f32 v10, -v7, v8, 1.0
	v_fmac_f32_e32 v8, v10, v8
	v_mul_f32_e32 v10, v9, v8
	v_fma_f32 v11, -v7, v10, v9
	v_fmac_f32_e32 v10, v11, v8
	v_fma_f32 v7, -v7, v10, v9
	v_div_fmas_f32 v7, v7, v8, v10
	v_div_fixup_f32 v5, v7, v6, v47
	ds_write_b32 v39, v5 offset:14336
	s_waitcnt vmcnt(1)
	v_mul_f32_e32 v6, 0xbfb8aa3b, v48
	v_exp_f32_e32 v6, v6
	s_nop 0
	v_add_f32_e32 v6, 1.0, v6
	v_div_scale_f32 v7, s[52:53], v6, v6, v48
	v_rcp_f32_e32 v8, v7
	v_div_scale_f32 v9, vcc, v48, v6, v48
	v_fma_f32 v10, -v7, v8, 1.0
	v_fmac_f32_e32 v8, v10, v8
	v_mul_f32_e32 v10, v9, v8
	v_fma_f32 v11, -v7, v10, v9
	v_fmac_f32_e32 v10, v11, v8
	v_fma_f32 v7, -v7, v10, v9
	v_div_fmas_f32 v7, v7, v8, v10
	v_div_fixup_f32 v5, v7, v6, v48
	ds_write_b32 v39, v5 offset:16384
	s_waitcnt vmcnt(0)
	v_mul_f32_e32 v6, 0xbfb8aa3b, v49
	v_exp_f32_e32 v6, v6
	s_nop 0
	v_add_f32_e32 v6, 1.0, v6
	v_div_scale_f32 v7, s[52:53], v6, v6, v49
	v_rcp_f32_e32 v8, v7
	v_div_scale_f32 v9, vcc, v49, v6, v49
	v_fma_f32 v10, -v7, v8, 1.0
	v_fmac_f32_e32 v8, v10, v8
	v_mul_f32_e32 v10, v9, v8
	v_fma_f32 v11, -v7, v10, v9
	v_fmac_f32_e32 v10, v11, v8
	v_fma_f32 v7, -v7, v10, v9
	v_div_fmas_f32 v7, v7, v8, v10
	v_div_fixup_f32 v5, v7, v6, v49
	ds_write_b32 v39, v5 offset:18432

.LBB0_13:
	s_mul_hi_i32 s48, s64, 0x38e38e39
	s_lshr_b32 s49, s48, 31
	s_ashr_i32 s48, s48, 3
	s_add_i32 s52, s48, s49
	s_mul_i32 s48, s52, 36
	s_sub_i32 s48, s64, s48
	s_lshl_b32 s48, s48, 8
	s_ashr_i32 s49, s48, 31
	s_mul_i32 s50, s52, 0x2400000
	s_lshl_b64 s[48:49], s[48:49], 2
	s_mul_hi_i32 s51, s52, 0x2400000
	s_add_u32 s50, s50, s48
	s_addc_u32 s51, s51, s49
	v_mov_b32_e32 v2, 0
	v_lshl_add_u64 v[34:35], v[30:31], 0, s[50:51]
	s_mov_b64 s[50:51], 0
	s_mov_b32 s53, s44
	v_mov_b32_e32 v3, v2
	v_mov_b32_e32 v4, v2
	v_mov_b32_e32 v5, v2
	v_mov_b32_e32 v6, v2
	v_mov_b32_e32 v7, v2
	v_mov_b32_e32 v8, v2
	v_mov_b32_e32 v9, v2
	v_mov_b32_e32 v10, v2
	v_mov_b32_e32 v11, v2
	v_mov_b32_e32 v12, v2
	v_mov_b32_e32 v13, v2
	v_mov_b32_e32 v14, v2
	v_mov_b32_e32 v15, v2
	v_mov_b32_e32 v16, v2
	v_mov_b32_e32 v17, v2
	v_mov_b32_e32 v18, v2
	v_mov_b32_e32 v19, v2
	v_mov_b32_e32 v20, v2
	v_mov_b32_e32 v21, v2
	v_mov_b64_e32 v[36:37], v[34:35]
	s_mov_b64 vcc, 0x9000
	s_mov_b32 s50, 0
	global_load_dwordx4 v[40:43], v[36:37], off nt
	v_lshl_add_u64 v[36:37], v[36:37], 0, vcc
	global_load_dwordx4 v[84:87], v[36:37], off nt
	v_lshl_add_u64 v[36:37], v[36:37], 0, vcc
	global_load_dwordx4 v[88:91], v[36:37], off nt
	v_lshl_add_u64 v[36:37], v[36:37], 0, vcc
	global_load_dwordx4 v[92:95], v[36:37], off nt
	v_lshl_add_u64 v[36:37], v[36:37], 0, vcc
	global_load_dwordx4 v[96:99], v[36:37], off nt
	v_lshl_add_u64 v[36:37], v[36:37], 0, vcc
	global_load_dwordx4 v[100:103], v[36:37], off nt
	v_lshl_add_u64 v[36:37], v[36:37], 0, vcc
	global_load_dwordx4 v[104:107], v[36:37], off nt
	v_lshl_add_u64 v[36:37], v[36:37], 0, vcc
	global_load_dwordx4 v[108:111], v[36:37], off nt
	v_lshl_add_u64 v[36:37], v[36:37], 0, vcc
.Ladaln_loop:
	global_load_dwordx4 v[128:131], v[36:37], off nt
	v_lshl_add_u64 v[36:37], v[36:37], 0, vcc
	global_load_dwordx4 v[132:135], v[36:37], off nt
	v_lshl_add_u64 v[36:37], v[36:37], 0, vcc
	global_load_dwordx4 v[136:139], v[36:37], off nt
	v_lshl_add_u64 v[36:37], v[36:37], 0, vcc
	global_load_dwordx4 v[140:143], v[36:37], off nt
	v_lshl_add_u64 v[36:37], v[36:37], 0, vcc
	global_load_dwordx4 v[144:147], v[36:37], off nt
	v_lshl_add_u64 v[36:37], v[36:37], 0, vcc
	global_load_dwordx4 v[148:151], v[36:37], off nt
	v_lshl_add_u64 v[36:37], v[36:37], 0, vcc
	global_load_dwordx4 v[152:155], v[36:37], off nt
	v_lshl_add_u64 v[36:37], v[36:37], 0, vcc
	global_load_dwordx4 v[156:159], v[36:37], off nt
	v_lshl_add_u64 v[36:37], v[36:37], 0, vcc
	v_mov_b32_e32 v24, s53
	s_add_i32 s53, s53, 32
	ds_read_b128 v[44:47], v24
	ds_read_b128 v[48:51], v24 offset:16
	ds_read_b128 v[52:55], v24 offset:4096
	ds_read_b128 v[56:59], v24 offset:4112
	ds_read_b128 v[60:63], v24 offset:8192
	ds_read_b128 v[64:67], v24 offset:8208
	ds_read_b128 v[68:71], v24 offset:12288
	ds_read_b128 v[72:75], v24 offset:12304
	ds_read_b128 v[76:79], v24 offset:16384
	ds_read_b128 v[80:83], v24 offset:16400
	s_waitcnt lgkmcnt(0)
	s_waitcnt vmcnt(15)
	v_pk_fma_f32 v[6:7], v[40:41], v[44:45], v[6:7] op_sel_hi:[1,0,1]
	v_pk_fma_f32 v[8:9], v[42:43], v[44:45], v[8:9] op_sel_hi:[1,0,1]
	v_pk_fma_f32 v[10:11], v[40:41], v[52:53], v[10:11] op_sel_hi:[1,0,1]
	v_pk_fma_f32 v[12:13], v[42:43], v[52:53], v[12:13] op_sel_hi:[1,0,1]
	v_pk_fma_f32 v[14:15], v[40:41], v[60:61], v[14:15] op_sel_hi:[1,0,1]
	v_pk_fma_f32 v[16:17], v[42:43], v[60:61], v[16:17] op_sel_hi:[1,0,1]
	v_pk_fma_f32 v[18:19], v[40:41], v[68:69], v[18:19] op_sel_hi:[1,0,1]
	v_pk_fma_f32 v[20:21], v[42:43], v[68:69], v[20:21] op_sel_hi:[1,0,1]
	v_pk_fma_f32 v[2:3], v[40:41], v[76:77], v[2:3] op_sel_hi:[1,0,1]
	v_pk_fma_f32 v[4:5], v[42:43], v[76:77], v[4:5] op_sel_hi:[1,0,1]
	s_waitcnt vmcnt(14)
	v_pk_fma_f32 v[6:7], v[84:85], v[44:45], v[6:7] op_sel:[0,1,0]
	v_pk_fma_f32 v[8:9], v[86:87], v[44:45], v[8:9] op_sel:[0,1,0]
	v_pk_fma_f32 v[10:11], v[84:85], v[52:53], v[10:11] op_sel:[0,1,0]
	v_pk_fma_f32 v[12:13], v[86:87], v[52:53], v[12:13] op_sel:[0,1,0]
	v_pk_fma_f32 v[14:15], v[84:85], v[60:61], v[14:15] op_sel:[0,1,0]
	v_pk_fma_f32 v[16:17], v[86:87], v[60:61], v[16:17] op_sel:[0,1,0]
	v_pk_fma_f32 v[18:19], v[84:85], v[68:69], v[18:19] op_sel:[0,1,0]
	v_pk_fma_f32 v[20:21], v[86:87], v[68:69], v[20:21] op_sel:[0,1,0]
	v_pk_fma_f32 v[2:3], v[84:85], v[76:77], v[2:3] op_sel:[0,1,0]
	v_pk_fma_f32 v[4:5], v[86:87], v[76:77], v[4:5] op_sel:[0,1,0]
	s_waitcnt vmcnt(13)
	v_pk_fma_f32 v[6:7], v[88:89], v[46:47], v[6:7] op_sel_hi:[1,0,1]
	v_pk_fma_f32 v[8:9], v[90:91], v[46:47], v[8:9] op_sel_hi:[1,0,1]
	v_pk_fma_f32 v[10:11], v[88:89], v[54:55], v[10:11] op_sel_hi:[1,0,1]
	v_pk_fma_f32 v[12:13], v[90:91], v[54:55], v[12:13] op_sel_hi:[1,0,1]
	v_pk_fma_f32 v[14:15], v[88:89], v[62:63], v[14:15] op_sel_hi:[1,0,1]
	v_pk_fma_f32 v[16:17], v[90:91], v[62:63], v[16:17] op_sel_hi:[1,0,1]
	v_pk_fma_f32 v[18:19], v[88:89], v[70:71], v[18:19] op_sel_hi:[1,0,1]
	v_pk_fma_f32 v[20:21], v[90:91], v[70:71], v[20:21] op_sel_hi:[1,0,1]
	v_pk_fma_f32 v[2:3], v[88:89], v[78:79], v[2:3] op_sel_hi:[1,0,1]
	v_pk_fma_f32 v[4:5], v[90:91], v[78:79], v[4:5] op_sel_hi:[1,0,1]
	s_waitcnt vmcnt(12)
	v_pk_fma_f32 v[6:7], v[92:93], v[46:47], v[6:7] op_sel:[0,1,0]
	v_pk_fma_f32 v[8:9], v[94:95], v[46:47], v[8:9] op_sel:[0,1,0]
	v_pk_fma_f32 v[10:11], v[92:93], v[54:55], v[10:11] op_sel:[0,1,0]
	v_pk_fma_f32 v[12:13], v[94:95], v[54:55], v[12:13] op_sel:[0,1,0]
	v_pk_fma_f32 v[14:15], v[92:93], v[62:63], v[14:15] op_sel:[0,1,0]
	v_pk_fma_f32 v[16:17], v[94:95], v[62:63], v[16:17] op_sel:[0,1,0]
	v_pk_fma_f32 v[18:19], v[92:93], v[70:71], v[18:19] op_sel:[0,1,0]
	v_pk_fma_f32 v[20:21], v[94:95], v[70:71], v[20:21] op_sel:[0,1,0]
	v_pk_fma_f32 v[2:3], v[92:93], v[78:79], v[2:3] op_sel:[0,1,0]
	v_pk_fma_f32 v[4:5], v[94:95], v[78:79], v[4:5] op_sel:[0,1,0]
	s_waitcnt vmcnt(11)
	v_pk_fma_f32 v[6:7], v[96:97], v[48:49], v[6:7] op_sel_hi:[1,0,1]
	v_pk_fma_f32 v[8:9], v[98:99], v[48:49], v[8:9] op_sel_hi:[1,0,1]
	v_pk_fma_f32 v[10:11], v[96:97], v[56:57], v[10:11] op_sel_hi:[1,0,1]
	v_pk_fma_f32 v[12:13], v[98:99], v[56:57], v[12:13] op_sel_hi:[1,0,1]
	v_pk_fma_f32 v[14:15], v[96:97], v[64:65], v[14:15] op_sel_hi:[1,0,1]
	v_pk_fma_f32 v[16:17], v[98:99], v[64:65], v[16:17] op_sel_hi:[1,0,1]
	v_pk_fma_f32 v[18:19], v[96:97], v[72:73], v[18:19] op_sel_hi:[1,0,1]
	v_pk_fma_f32 v[20:21], v[98:99], v[72:73], v[20:21] op_sel_hi:[1,0,1]
	v_pk_fma_f32 v[2:3], v[96:97], v[80:81], v[2:3] op_sel_hi:[1,0,1]
	v_pk_fma_f32 v[4:5], v[98:99], v[80:81], v[4:5] op_sel_hi:[1,0,1]
	s_waitcnt vmcnt(10)
	v_pk_fma_f32 v[6:7], v[100:101], v[48:49], v[6:7] op_sel:[0,1,0]
	v_pk_fma_f32 v[8:9], v[102:103], v[48:49], v[8:9] op_sel:[0,1,0]
	v_pk_fma_f32 v[10:11], v[100:101], v[56:57], v[10:11] op_sel:[0,1,0]
	v_pk_fma_f32 v[12:13], v[102:103], v[56:57], v[12:13] op_sel:[0,1,0]
	v_pk_fma_f32 v[14:15], v[100:101], v[64:65], v[14:15] op_sel:[0,1,0]
	v_pk_fma_f32 v[16:17], v[102:103], v[64:65], v[16:17] op_sel:[0,1,0]
	v_pk_fma_f32 v[18:19], v[100:101], v[72:73], v[18:19] op_sel:[0,1,0]
	v_pk_fma_f32 v[20:21], v[102:103], v[72:73], v[20:21] op_sel:[0,1,0]
	v_pk_fma_f32 v[2:3], v[100:101], v[80:81], v[2:3] op_sel:[0,1,0]
	v_pk_fma_f32 v[4:5], v[102:103], v[80:81], v[4:5] op_sel:[0,1,0]
	s_waitcnt vmcnt(9)
	v_pk_fma_f32 v[6:7], v[104:105], v[50:51], v[6:7] op_sel_hi:[1,0,1]
	v_pk_fma_f32 v[8:9], v[106:107], v[50:51], v[8:9] op_sel_hi:[1,0,1]
	v_pk_fma_f32 v[10:11], v[104:105], v[58:59], v[10:11] op_sel_hi:[1,0,1]
	v_pk_fma_f32 v[12:13], v[106:107], v[58:59], v[12:13] op_sel_hi:[1,0,1]
	v_pk_fma_f32 v[14:15], v[104:105], v[66:67], v[14:15] op_sel_hi:[1,0,1]
	v_pk_fma_f32 v[16:17], v[106:107], v[66:67], v[16:17] op_sel_hi:[1,0,1]
	v_pk_fma_f32 v[18:19], v[104:105], v[74:75], v[18:19] op_sel_hi:[1,0,1]
	v_pk_fma_f32 v[20:21], v[106:107], v[74:75], v[20:21] op_sel_hi:[1,0,1]
	v_pk_fma_f32 v[2:3], v[104:105], v[82:83], v[2:3] op_sel_hi:[1,0,1]
	v_pk_fma_f32 v[4:5], v[106:107], v[82:83], v[4:5] op_sel_hi:[1,0,1]
	s_waitcnt vmcnt(8)
	v_pk_fma_f32 v[6:7], v[108:109], v[50:51], v[6:7] op_sel:[0,1,0]
	v_pk_fma_f32 v[8:9], v[110:111], v[50:51], v[8:9] op_sel:[0,1,0]
	v_pk_fma_f32 v[10:11], v[108:109], v[58:59], v[10:11] op_sel:[0,1,0]
	v_pk_fma_f32 v[12:13], v[110:111], v[58:59], v[12:13] op_sel:[0,1,0]
	v_pk_fma_f32 v[14:15], v[108:109], v[66:67], v[14:15] op_sel:[0,1,0]
	v_pk_fma_f32 v[16:17], v[110:111], v[66:67], v[16:17] op_sel:[0,1,0]
	v_pk_fma_f32 v[18:19], v[108:109], v[74:75], v[18:19] op_sel:[0,1,0]
	v_pk_fma_f32 v[20:21], v[110:111], v[74:75], v[20:21] op_sel:[0,1,0]
	v_pk_fma_f32 v[2:3], v[108:109], v[82:83], v[2:3] op_sel:[0,1,0]
	v_pk_fma_f32 v[4:5], v[110:111], v[82:83], v[4:5] op_sel:[0,1,0]
	global_load_dwordx4 v[40:43], v[36:37], off nt
	v_lshl_add_u64 v[36:37], v[36:37], 0, vcc
	global_load_dwordx4 v[84:87], v[36:37], off nt
	v_lshl_add_u64 v[36:37], v[36:37], 0, vcc
	global_load_dwordx4 v[88:91], v[36:37], off nt
	v_lshl_add_u64 v[36:37], v[36:37], 0, vcc
	global_load_dwordx4 v[92:95], v[36:37], off nt
	v_lshl_add_u64 v[36:37], v[36:37], 0, vcc
	global_load_dwordx4 v[96:99], v[36:37], off nt
	v_lshl_add_u64 v[36:37], v[36:37], 0, vcc
	global_load_dwordx4 v[100:103], v[36:37], off nt
	v_lshl_add_u64 v[36:37], v[36:37], 0, vcc
	global_load_dwordx4 v[104:107], v[36:37], off nt
	v_lshl_add_u64 v[36:37], v[36:37], 0, vcc
	global_load_dwordx4 v[108:111], v[36:37], off nt
	v_lshl_add_u64 v[36:37], v[36:37], 0, vcc
	v_mov_b32_e32 v24, s53
	s_add_i32 s53, s53, 32
	ds_read_b128 v[44:47], v24
	ds_read_b128 v[48:51], v24 offset:16
	ds_read_b128 v[52:55], v24 offset:4096
	ds_read_b128 v[56:59], v24 offset:4112
	ds_read_b128 v[60:63], v24 offset:8192
	ds_read_b128 v[64:67], v24 offset:8208
	ds_read_b128 v[68:71], v24 offset:12288
	ds_read_b128 v[72:75], v24 offset:12304
	ds_read_b128 v[76:79], v24 offset:16384
	ds_read_b128 v[80:83], v24 offset:16400
	s_waitcnt lgkmcnt(0)
	s_waitcnt vmcnt(15)
	v_pk_fma_f32 v[6:7], v[128:129], v[44:45], v[6:7] op_sel_hi:[1,0,1]
	v_pk_fma_f32 v[8:9], v[130:131], v[44:45], v[8:9] op_sel_hi:[1,0,1]
	v_pk_fma_f32 v[10:11], v[128:129], v[52:53], v[10:11] op_sel_hi:[1,0,1]
	v_pk_fma_f32 v[12:13], v[130:131], v[52:53], v[12:13] op_sel_hi:[1,0,1]
	v_pk_fma_f32 v[14:15], v[128:129], v[60:61], v[14:15] op_sel_hi:[1,0,1]
	v_pk_fma_f32 v[16:17], v[130:131], v[60:61], v[16:17] op_sel_hi:[1,0,1]
	v_pk_fma_f32 v[18:19], v[128:129], v[68:69], v[18:19] op_sel_hi:[1,0,1]
	v_pk_fma_f32 v[20:21], v[130:131], v[68:69], v[20:21] op_sel_hi:[1,0,1]
	v_pk_fma_f32 v[2:3], v[128:129], v[76:77], v[2:3] op_sel_hi:[1,0,1]
	v_pk_fma_f32 v[4:5], v[130:131], v[76:77], v[4:5] op_sel_hi:[1,0,1]
	s_waitcnt vmcnt(14)
	v_pk_fma_f32 v[6:7], v[132:133], v[44:45], v[6:7] op_sel:[0,1,0]
	v_pk_fma_f32 v[8:9], v[134:135], v[44:45], v[8:9] op_sel:[0,1,0]
	v_pk_fma_f32 v[10:11], v[132:133], v[52:53], v[10:11] op_sel:[0,1,0]
	v_pk_fma_f32 v[12:13], v[134:135], v[52:53], v[12:13] op_sel:[0,1,0]
	v_pk_fma_f32 v[14:15], v[132:133], v[60:61], v[14:15] op_sel:[0,1,0]
	v_pk_fma_f32 v[16:17], v[134:135], v[60:61], v[16:17] op_sel:[0,1,0]
	v_pk_fma_f32 v[18:19], v[132:133], v[68:69], v[18:19] op_sel:[0,1,0]
	v_pk_fma_f32 v[20:21], v[134:135], v[68:69], v[20:21] op_sel:[0,1,0]
	v_pk_fma_f32 v[2:3], v[132:133], v[76:77], v[2:3] op_sel:[0,1,0]
	v_pk_fma_f32 v[4:5], v[134:135], v[76:77], v[4:5] op_sel:[0,1,0]
	s_waitcnt vmcnt(13)
	v_pk_fma_f32 v[6:7], v[136:137], v[46:47], v[6:7] op_sel_hi:[1,0,1]
	v_pk_fma_f32 v[8:9], v[138:139], v[46:47], v[8:9] op_sel_hi:[1,0,1]
	v_pk_fma_f32 v[10:11], v[136:137], v[54:55], v[10:11] op_sel_hi:[1,0,1]
	v_pk_fma_f32 v[12:13], v[138:139], v[54:55], v[12:13] op_sel_hi:[1,0,1]
	v_pk_fma_f32 v[14:15], v[136:137], v[62:63], v[14:15] op_sel_hi:[1,0,1]
	v_pk_fma_f32 v[16:17], v[138:139], v[62:63], v[16:17] op_sel_hi:[1,0,1]
	v_pk_fma_f32 v[18:19], v[136:137], v[70:71], v[18:19] op_sel_hi:[1,0,1]
	v_pk_fma_f32 v[20:21], v[138:139], v[70:71], v[20:21] op_sel_hi:[1,0,1]
	v_pk_fma_f32 v[2:3], v[136:137], v[78:79], v[2:3] op_sel_hi:[1,0,1]
	v_pk_fma_f32 v[4:5], v[138:139], v[78:79], v[4:5] op_sel_hi:[1,0,1]
	s_waitcnt vmcnt(12)
	v_pk_fma_f32 v[6:7], v[140:141], v[46:47], v[6:7] op_sel:[0,1,0]
	v_pk_fma_f32 v[8:9], v[142:143], v[46:47], v[8:9] op_sel:[0,1,0]
	v_pk_fma_f32 v[10:11], v[140:141], v[54:55], v[10:11] op_sel:[0,1,0]
	v_pk_fma_f32 v[12:13], v[142:143], v[54:55], v[12:13] op_sel:[0,1,0]
	v_pk_fma_f32 v[14:15], v[140:141], v[62:63], v[14:15] op_sel:[0,1,0]
	v_pk_fma_f32 v[16:17], v[142:143], v[62:63], v[16:17] op_sel:[0,1,0]
	v_pk_fma_f32 v[18:19], v[140:141], v[70:71], v[18:19] op_sel:[0,1,0]
	v_pk_fma_f32 v[20:21], v[142:143], v[70:71], v[20:21] op_sel:[0,1,0]
	v_pk_fma_f32 v[2:3], v[140:141], v[78:79], v[2:3] op_sel:[0,1,0]
	v_pk_fma_f32 v[4:5], v[142:143], v[78:79], v[4:5] op_sel:[0,1,0]
	s_waitcnt vmcnt(11)
	v_pk_fma_f32 v[6:7], v[144:145], v[48:49], v[6:7] op_sel_hi:[1,0,1]
	v_pk_fma_f32 v[8:9], v[146:147], v[48:49], v[8:9] op_sel_hi:[1,0,1]
	v_pk_fma_f32 v[10:11], v[144:145], v[56:57], v[10:11] op_sel_hi:[1,0,1]
	v_pk_fma_f32 v[12:13], v[146:147], v[56:57], v[12:13] op_sel_hi:[1,0,1]
	v_pk_fma_f32 v[14:15], v[144:145], v[64:65], v[14:15] op_sel_hi:[1,0,1]
	v_pk_fma_f32 v[16:17], v[146:147], v[64:65], v[16:17] op_sel_hi:[1,0,1]
	v_pk_fma_f32 v[18:19], v[144:145], v[72:73], v[18:19] op_sel_hi:[1,0,1]
	v_pk_fma_f32 v[20:21], v[146:147], v[72:73], v[20:21] op_sel_hi:[1,0,1]
	v_pk_fma_f32 v[2:3], v[144:145], v[80:81], v[2:3] op_sel_hi:[1,0,1]
	v_pk_fma_f32 v[4:5], v[146:147], v[80:81], v[4:5] op_sel_hi:[1,0,1]
	s_waitcnt vmcnt(10)
	v_pk_fma_f32 v[6:7], v[148:149], v[48:49], v[6:7] op_sel:[0,1,0]
	v_pk_fma_f32 v[8:9], v[150:151], v[48:49], v[8:9] op_sel:[0,1,0]
	v_pk_fma_f32 v[10:11], v[148:149], v[56:57], v[10:11] op_sel:[0,1,0]
	v_pk_fma_f32 v[12:13], v[150:151], v[56:57], v[12:13] op_sel:[0,1,0]
	v_pk_fma_f32 v[14:15], v[148:149], v[64:65], v[14:15] op_sel:[0,1,0]
	v_pk_fma_f32 v[16:17], v[150:151], v[64:65], v[16:17] op_sel:[0,1,0]
	v_pk_fma_f32 v[18:19], v[148:149], v[72:73], v[18:19] op_sel:[0,1,0]
	v_pk_fma_f32 v[20:21], v[150:151], v[72:73], v[20:21] op_sel:[0,1,0]
	v_pk_fma_f32 v[2:3], v[148:149], v[80:81], v[2:3] op_sel:[0,1,0]
	v_pk_fma_f32 v[4:5], v[150:151], v[80:81], v[4:5] op_sel:[0,1,0]
	s_waitcnt vmcnt(9)
	v_pk_fma_f32 v[6:7], v[152:153], v[50:51], v[6:7] op_sel_hi:[1,0,1]
	v_pk_fma_f32 v[8:9], v[154:155], v[50:51], v[8:9] op_sel_hi:[1,0,1]
	v_pk_fma_f32 v[10:11], v[152:153], v[58:59], v[10:11] op_sel_hi:[1,0,1]
	v_pk_fma_f32 v[12:13], v[154:155], v[58:59], v[12:13] op_sel_hi:[1,0,1]
	v_pk_fma_f32 v[14:15], v[152:153], v[66:67], v[14:15] op_sel_hi:[1,0,1]
	v_pk_fma_f32 v[16:17], v[154:155], v[66:67], v[16:17] op_sel_hi:[1,0,1]
	v_pk_fma_f32 v[18:19], v[152:153], v[74:75], v[18:19] op_sel_hi:[1,0,1]
	v_pk_fma_f32 v[20:21], v[154:155], v[74:75], v[20:21] op_sel_hi:[1,0,1]
	v_pk_fma_f32 v[2:3], v[152:153], v[82:83], v[2:3] op_sel_hi:[1,0,1]
	v_pk_fma_f32 v[4:5], v[154:155], v[82:83], v[4:5] op_sel_hi:[1,0,1]
	s_waitcnt vmcnt(8)
	v_pk_fma_f32 v[6:7], v[156:157], v[50:51], v[6:7] op_sel:[0,1,0]
	v_pk_fma_f32 v[8:9], v[158:159], v[50:51], v[8:9] op_sel:[0,1,0]
	v_pk_fma_f32 v[10:11], v[156:157], v[58:59], v[10:11] op_sel:[0,1,0]
	v_pk_fma_f32 v[12:13], v[158:159], v[58:59], v[12:13] op_sel:[0,1,0]
	v_pk_fma_f32 v[14:15], v[156:157], v[66:67], v[14:15] op_sel:[0,1,0]
	v_pk_fma_f32 v[16:17], v[158:159], v[66:67], v[16:17] op_sel:[0,1,0]
	v_pk_fma_f32 v[18:19], v[156:157], v[74:75], v[18:19] op_sel:[0,1,0]
	v_pk_fma_f32 v[20:21], v[158:159], v[74:75], v[20:21] op_sel:[0,1,0]
	v_pk_fma_f32 v[2:3], v[156:157], v[82:83], v[2:3] op_sel:[0,1,0]
	v_pk_fma_f32 v[4:5], v[158:159], v[82:83], v[4:5] op_sel:[0,1,0]
	s_add_i32 s50, s50, 1
	s_cmp_lg_u32 s50, 7
	s_cbranch_scc1 .Ladaln_loop
	global_load_dwordx4 v[128:131], v[36:37], off nt
	v_lshl_add_u64 v[36:37], v[36:37], 0, vcc
	global_load_dwordx4 v[132:135], v[36:37], off nt
	v_lshl_add_u64 v[36:37], v[36:37], 0, vcc
	global_load_dwordx4 v[136:139], v[36:37], off nt
	v_lshl_add_u64 v[36:37], v[36:37], 0, vcc
	global_load_dwordx4 v[140:143], v[36:37], off nt
	v_lshl_add_u64 v[36:37], v[36:37], 0, vcc
	global_load_dwordx4 v[144:147], v[36:37], off nt
	v_lshl_add_u64 v[36:37], v[36:37], 0, vcc
	global_load_dwordx4 v[148:151], v[36:37], off nt
	v_lshl_add_u64 v[36:37], v[36:37], 0, vcc
	global_load_dwordx4 v[152:155], v[36:37], off nt
	v_lshl_add_u64 v[36:37], v[36:37], 0, vcc
	global_load_dwordx4 v[156:159], v[36:37], off nt
	v_lshl_add_u64 v[36:37], v[36:37], 0, vcc
	v_mov_b32_e32 v24, s53
	s_add_i32 s53, s53, 32
	ds_read_b128 v[44:47], v24
	ds_read_b128 v[48:51], v24 offset:16
	ds_read_b128 v[52:55], v24 offset:4096
	ds_read_b128 v[56:59], v24 offset:4112
	ds_read_b128 v[60:63], v24 offset:8192
	ds_read_b128 v[64:67], v24 offset:8208
	ds_read_b128 v[68:71], v24 offset:12288
	ds_read_b128 v[72:75], v24 offset:12304
	ds_read_b128 v[76:79], v24 offset:16384
	ds_read_b128 v[80:83], v24 offset:16400
	s_waitcnt lgkmcnt(0)
	s_waitcnt vmcnt(15)
	v_pk_fma_f32 v[6:7], v[40:41], v[44:45], v[6:7] op_sel_hi:[1,0,1]
	v_pk_fma_f32 v[8:9], v[42:43], v[44:45], v[8:9] op_sel_hi:[1,0,1]
	v_pk_fma_f32 v[10:11], v[40:41], v[52:53], v[10:11] op_sel_hi:[1,0,1]
	v_pk_fma_f32 v[12:13], v[42:43], v[52:53], v[12:13] op_sel_hi:[1,0,1]
	v_pk_fma_f32 v[14:15], v[40:41], v[60:61], v[14:15] op_sel_hi:[1,0,1]
	v_pk_fma_f32 v[16:17], v[42:43], v[60:61], v[16:17] op_sel_hi:[1,0,1]
	v_pk_fma_f32 v[18:19], v[40:41], v[68:69], v[18:19] op_sel_hi:[1,0,1]
	v_pk_fma_f32 v[20:21], v[42:43], v[68:69], v[20:21] op_sel_hi:[1,0,1]
	v_pk_fma_f32 v[2:3], v[40:41], v[76:77], v[2:3] op_sel_hi:[1,0,1]
	v_pk_fma_f32 v[4:5], v[42:43], v[76:77], v[4:5] op_sel_hi:[1,0,1]
	s_waitcnt vmcnt(14)
	v_pk_fma_f32 v[6:7], v[84:85], v[44:45], v[6:7] op_sel:[0,1,0]
	v_pk_fma_f32 v[8:9], v[86:87], v[44:45], v[8:9] op_sel:[0,1,0]
	v_pk_fma_f32 v[10:11], v[84:85], v[52:53], v[10:11] op_sel:[0,1,0]
	v_pk_fma_f32 v[12:13], v[86:87], v[52:53], v[12:13] op_sel:[0,1,0]
	v_pk_fma_f32 v[14:15], v[84:85], v[60:61], v[14:15] op_sel:[0,1,0]
	v_pk_fma_f32 v[16:17], v[86:87], v[60:61], v[16:17] op_sel:[0,1,0]
	v_pk_fma_f32 v[18:19], v[84:85], v[68:69], v[18:19] op_sel:[0,1,0]
	v_pk_fma_f32 v[20:21], v[86:87], v[68:69], v[20:21] op_sel:[0,1,0]
	v_pk_fma_f32 v[2:3], v[84:85], v[76:77], v[2:3] op_sel:[0,1,0]
	v_pk_fma_f32 v[4:5], v[86:87], v[76:77], v[4:5] op_sel:[0,1,0]
	s_waitcnt vmcnt(13)
	v_pk_fma_f32 v[6:7], v[88:89], v[46:47], v[6:7] op_sel_hi:[1,0,1]
	v_pk_fma_f32 v[8:9], v[90:91], v[46:47], v[8:9] op_sel_hi:[1,0,1]
	v_pk_fma_f32 v[10:11], v[88:89], v[54:55], v[10:11] op_sel_hi:[1,0,1]
	v_pk_fma_f32 v[12:13], v[90:91], v[54:55], v[12:13] op_sel_hi:[1,0,1]
	v_pk_fma_f32 v[14:15], v[88:89], v[62:63], v[14:15] op_sel_hi:[1,0,1]
	v_pk_fma_f32 v[16:17], v[90:91], v[62:63], v[16:17] op_sel_hi:[1,0,1]
	v_pk_fma_f32 v[18:19], v[88:89], v[70:71], v[18:19] op_sel_hi:[1,0,1]
	v_pk_fma_f32 v[20:21], v[90:91], v[70:71], v[20:21] op_sel_hi:[1,0,1]
	v_pk_fma_f32 v[2:3], v[88:89], v[78:79], v[2:3] op_sel_hi:[1,0,1]
	v_pk_fma_f32 v[4:5], v[90:91], v[78:79], v[4:5] op_sel_hi:[1,0,1]
	s_waitcnt vmcnt(12)
	v_pk_fma_f32 v[6:7], v[92:93], v[46:47], v[6:7] op_sel:[0,1,0]
	v_pk_fma_f32 v[8:9], v[94:95], v[46:47], v[8:9] op_sel:[0,1,0]
	v_pk_fma_f32 v[10:11], v[92:93], v[54:55], v[10:11] op_sel:[0,1,0]
	v_pk_fma_f32 v[12:13], v[94:95], v[54:55], v[12:13] op_sel:[0,1,0]
	v_pk_fma_f32 v[14:15], v[92:93], v[62:63], v[14:15] op_sel:[0,1,0]
	v_pk_fma_f32 v[16:17], v[94:95], v[62:63], v[16:17] op_sel:[0,1,0]
	v_pk_fma_f32 v[18:19], v[92:93], v[70:71], v[18:19] op_sel:[0,1,0]
	v_pk_fma_f32 v[20:21], v[94:95], v[70:71], v[20:21] op_sel:[0,1,0]
	v_pk_fma_f32 v[2:3], v[92:93], v[78:79], v[2:3] op_sel:[0,1,0]
	v_pk_fma_f32 v[4:5], v[94:95], v[78:79], v[4:5] op_sel:[0,1,0]
	s_waitcnt vmcnt(11)
	v_pk_fma_f32 v[6:7], v[96:97], v[48:49], v[6:7] op_sel_hi:[1,0,1]
	v_pk_fma_f32 v[8:9], v[98:99], v[48:49], v[8:9] op_sel_hi:[1,0,1]
	v_pk_fma_f32 v[10:11], v[96:97], v[56:57], v[10:11] op_sel_hi:[1,0,1]
	v_pk_fma_f32 v[12:13], v[98:99], v[56:57], v[12:13] op_sel_hi:[1,0,1]
	v_pk_fma_f32 v[14:15], v[96:97], v[64:65], v[14:15] op_sel_hi:[1,0,1]
	v_pk_fma_f32 v[16:17], v[98:99], v[64:65], v[16:17] op_sel_hi:[1,0,1]
	v_pk_fma_f32 v[18:19], v[96:97], v[72:73], v[18:19] op_sel_hi:[1,0,1]
	v_pk_fma_f32 v[20:21], v[98:99], v[72:73], v[20:21] op_sel_hi:[1,0,1]
	v_pk_fma_f32 v[2:3], v[96:97], v[80:81], v[2:3] op_sel_hi:[1,0,1]
	v_pk_fma_f32 v[4:5], v[98:99], v[80:81], v[4:5] op_sel_hi:[1,0,1]
	s_waitcnt vmcnt(10)
	v_pk_fma_f32 v[6:7], v[100:101], v[48:49], v[6:7] op_sel:[0,1,0]
	v_pk_fma_f32 v[8:9], v[102:103], v[48:49], v[8:9] op_sel:[0,1,0]
	v_pk_fma_f32 v[10:11], v[100:101], v[56:57], v[10:11] op_sel:[0,1,0]
	v_pk_fma_f32 v[12:13], v[102:103], v[56:57], v[12:13] op_sel:[0,1,0]
	v_pk_fma_f32 v[14:15], v[100:101], v[64:65], v[14:15] op_sel:[0,1,0]
	v_pk_fma_f32 v[16:17], v[102:103], v[64:65], v[16:17] op_sel:[0,1,0]
	v_pk_fma_f32 v[18:19], v[100:101], v[72:73], v[18:19] op_sel:[0,1,0]
	v_pk_fma_f32 v[20:21], v[102:103], v[72:73], v[20:21] op_sel:[0,1,0]
	v_pk_fma_f32 v[2:3], v[100:101], v[80:81], v[2:3] op_sel:[0,1,0]
	v_pk_fma_f32 v[4:5], v[102:103], v[80:81], v[4:5] op_sel:[0,1,0]
	s_waitcnt vmcnt(9)
	v_pk_fma_f32 v[6:7], v[104:105], v[50:51], v[6:7] op_sel_hi:[1,0,1]
	v_pk_fma_f32 v[8:9], v[106:107], v[50:51], v[8:9] op_sel_hi:[1,0,1]
	v_pk_fma_f32 v[10:11], v[104:105], v[58:59], v[10:11] op_sel_hi:[1,0,1]
	v_pk_fma_f32 v[12:13], v[106:107], v[58:59], v[12:13] op_sel_hi:[1,0,1]
	v_pk_fma_f32 v[14:15], v[104:105], v[66:67], v[14:15] op_sel_hi:[1,0,1]
	v_pk_fma_f32 v[16:17], v[106:107], v[66:67], v[16:17] op_sel_hi:[1,0,1]
	v_pk_fma_f32 v[18:19], v[104:105], v[74:75], v[18:19] op_sel_hi:[1,0,1]
	v_pk_fma_f32 v[20:21], v[106:107], v[74:75], v[20:21] op_sel_hi:[1,0,1]
	v_pk_fma_f32 v[2:3], v[104:105], v[82:83], v[2:3] op_sel_hi:[1,0,1]
	v_pk_fma_f32 v[4:5], v[106:107], v[82:83], v[4:5] op_sel_hi:[1,0,1]
	s_waitcnt vmcnt(8)
	v_pk_fma_f32 v[6:7], v[108:109], v[50:51], v[6:7] op_sel:[0,1,0]
	v_pk_fma_f32 v[8:9], v[110:111], v[50:51], v[8:9] op_sel:[0,1,0]
	v_pk_fma_f32 v[10:11], v[108:109], v[58:59], v[10:11] op_sel:[0,1,0]
	v_pk_fma_f32 v[12:13], v[110:111], v[58:59], v[12:13] op_sel:[0,1,0]
	v_pk_fma_f32 v[14:15], v[108:109], v[66:67], v[14:15] op_sel:[0,1,0]
	v_pk_fma_f32 v[16:17], v[110:111], v[66:67], v[16:17] op_sel:[0,1,0]
	v_pk_fma_f32 v[18:19], v[108:109], v[74:75], v[18:19] op_sel:[0,1,0]
	v_pk_fma_f32 v[20:21], v[110:111], v[74:75], v[20:21] op_sel:[0,1,0]
	v_pk_fma_f32 v[2:3], v[108:109], v[82:83], v[2:3] op_sel:[0,1,0]
	v_pk_fma_f32 v[4:5], v[110:111], v[82:83], v[4:5] op_sel:[0,1,0]
	v_mov_b32_e32 v24, s53
	s_add_i32 s53, s53, 32
	ds_read_b128 v[44:47], v24
	ds_read_b128 v[48:51], v24 offset:16
	ds_read_b128 v[52:55], v24 offset:4096
	ds_read_b128 v[56:59], v24 offset:4112
	ds_read_b128 v[60:63], v24 offset:8192
	ds_read_b128 v[64:67], v24 offset:8208
	ds_read_b128 v[68:71], v24 offset:12288
	ds_read_b128 v[72:75], v24 offset:12304
	ds_read_b128 v[76:79], v24 offset:16384
	ds_read_b128 v[80:83], v24 offset:16400
	s_waitcnt lgkmcnt(0)
	s_waitcnt vmcnt(7)
	v_pk_fma_f32 v[6:7], v[128:129], v[44:45], v[6:7] op_sel_hi:[1,0,1]
	v_pk_fma_f32 v[8:9], v[130:131], v[44:45], v[8:9] op_sel_hi:[1,0,1]
	v_pk_fma_f32 v[10:11], v[128:129], v[52:53], v[10:11] op_sel_hi:[1,0,1]
	v_pk_fma_f32 v[12:13], v[130:131], v[52:53], v[12:13] op_sel_hi:[1,0,1]
	v_pk_fma_f32 v[14:15], v[128:129], v[60:61], v[14:15] op_sel_hi:[1,0,1]
	v_pk_fma_f32 v[16:17], v[130:131], v[60:61], v[16:17] op_sel_hi:[1,0,1]
	v_pk_fma_f32 v[18:19], v[128:129], v[68:69], v[18:19] op_sel_hi:[1,0,1]
	v_pk_fma_f32 v[20:21], v[130:131], v[68:69], v[20:21] op_sel_hi:[1,0,1]
	v_pk_fma_f32 v[2:3], v[128:129], v[76:77], v[2:3] op_sel_hi:[1,0,1]
	v_pk_fma_f32 v[4:5], v[130:131], v[76:77], v[4:5] op_sel_hi:[1,0,1]
	s_waitcnt vmcnt(6)
	v_pk_fma_f32 v[6:7], v[132:133], v[44:45], v[6:7] op_sel:[0,1,0]
	v_pk_fma_f32 v[8:9], v[134:135], v[44:45], v[8:9] op_sel:[0,1,0]
	v_pk_fma_f32 v[10:11], v[132:133], v[52:53], v[10:11] op_sel:[0,1,0]
	v_pk_fma_f32 v[12:13], v[134:135], v[52:53], v[12:13] op_sel:[0,1,0]
	v_pk_fma_f32 v[14:15], v[132:133], v[60:61], v[14:15] op_sel:[0,1,0]
	v_pk_fma_f32 v[16:17], v[134:135], v[60:61], v[16:17] op_sel:[0,1,0]
	v_pk_fma_f32 v[18:19], v[132:133], v[68:69], v[18:19] op_sel:[0,1,0]
	v_pk_fma_f32 v[20:21], v[134:135], v[68:69], v[20:21] op_sel:[0,1,0]
	v_pk_fma_f32 v[2:3], v[132:133], v[76:77], v[2:3] op_sel:[0,1,0]
	v_pk_fma_f32 v[4:5], v[134:135], v[76:77], v[4:5] op_sel:[0,1,0]
	s_waitcnt vmcnt(5)
	v_pk_fma_f32 v[6:7], v[136:137], v[46:47], v[6:7] op_sel_hi:[1,0,1]
	v_pk_fma_f32 v[8:9], v[138:139], v[46:47], v[8:9] op_sel_hi:[1,0,1]
	v_pk_fma_f32 v[10:11], v[136:137], v[54:55], v[10:11] op_sel_hi:[1,0,1]
	v_pk_fma_f32 v[12:13], v[138:139], v[54:55], v[12:13] op_sel_hi:[1,0,1]
	v_pk_fma_f32 v[14:15], v[136:137], v[62:63], v[14:15] op_sel_hi:[1,0,1]
	v_pk_fma_f32 v[16:17], v[138:139], v[62:63], v[16:17] op_sel_hi:[1,0,1]
	v_pk_fma_f32 v[18:19], v[136:137], v[70:71], v[18:19] op_sel_hi:[1,0,1]
	v_pk_fma_f32 v[20:21], v[138:139], v[70:71], v[20:21] op_sel_hi:[1,0,1]
	v_pk_fma_f32 v[2:3], v[136:137], v[78:79], v[2:3] op_sel_hi:[1,0,1]
	v_pk_fma_f32 v[4:5], v[138:139], v[78:79], v[4:5] op_sel_hi:[1,0,1]
	s_waitcnt vmcnt(4)
	v_pk_fma_f32 v[6:7], v[140:141], v[46:47], v[6:7] op_sel:[0,1,0]
	v_pk_fma_f32 v[8:9], v[142:143], v[46:47], v[8:9] op_sel:[0,1,0]
	v_pk_fma_f32 v[10:11], v[140:141], v[54:55], v[10:11] op_sel:[0,1,0]
	v_pk_fma_f32 v[12:13], v[142:143], v[54:55], v[12:13] op_sel:[0,1,0]
	v_pk_fma_f32 v[14:15], v[140:141], v[62:63], v[14:15] op_sel:[0,1,0]
	v_pk_fma_f32 v[16:17], v[142:143], v[62:63], v[16:17] op_sel:[0,1,0]
	v_pk_fma_f32 v[18:19], v[140:141], v[70:71], v[18:19] op_sel:[0,1,0]
	v_pk_fma_f32 v[20:21], v[142:143], v[70:71], v[20:21] op_sel:[0,1,0]
	v_pk_fma_f32 v[2:3], v[140:141], v[78:79], v[2:3] op_sel:[0,1,0]
	v_pk_fma_f32 v[4:5], v[142:143], v[78:79], v[4:5] op_sel:[0,1,0]
	s_waitcnt vmcnt(3)
	v_pk_fma_f32 v[6:7], v[144:145], v[48:49], v[6:7] op_sel_hi:[1,0,1]
	v_pk_fma_f32 v[8:9], v[146:147], v[48:49], v[8:9] op_sel_hi:[1,0,1]
	v_pk_fma_f32 v[10:11], v[144:145], v[56:57], v[10:11] op_sel_hi:[1,0,1]
	v_pk_fma_f32 v[12:13], v[146:147], v[56:57], v[12:13] op_sel_hi:[1,0,1]
	v_pk_fma_f32 v[14:15], v[144:145], v[64:65], v[14:15] op_sel_hi:[1,0,1]
	v_pk_fma_f32 v[16:17], v[146:147], v[64:65], v[16:17] op_sel_hi:[1,0,1]
	v_pk_fma_f32 v[18:19], v[144:145], v[72:73], v[18:19] op_sel_hi:[1,0,1]
	v_pk_fma_f32 v[20:21], v[146:147], v[72:73], v[20:21] op_sel_hi:[1,0,1]
	v_pk_fma_f32 v[2:3], v[144:145], v[80:81], v[2:3] op_sel_hi:[1,0,1]
	v_pk_fma_f32 v[4:5], v[146:147], v[80:81], v[4:5] op_sel_hi:[1,0,1]
	s_waitcnt vmcnt(2)
	v_pk_fma_f32 v[6:7], v[148:149], v[48:49], v[6:7] op_sel:[0,1,0]
	v_pk_fma_f32 v[8:9], v[150:151], v[48:49], v[8:9] op_sel:[0,1,0]
	v_pk_fma_f32 v[10:11], v[148:149], v[56:57], v[10:11] op_sel:[0,1,0]
	v_pk_fma_f32 v[12:13], v[150:151], v[56:57], v[12:13] op_sel:[0,1,0]
	v_pk_fma_f32 v[14:15], v[148:149], v[64:65], v[14:15] op_sel:[0,1,0]
	v_pk_fma_f32 v[16:17], v[150:151], v[64:65], v[16:17] op_sel:[0,1,0]
	v_pk_fma_f32 v[18:19], v[148:149], v[72:73], v[18:19] op_sel:[0,1,0]
	v_pk_fma_f32 v[20:21], v[150:151], v[72:73], v[20:21] op_sel:[0,1,0]
	v_pk_fma_f32 v[2:3], v[148:149], v[80:81], v[2:3] op_sel:[0,1,0]
	v_pk_fma_f32 v[4:5], v[150:151], v[80:81], v[4:5] op_sel:[0,1,0]
	s_waitcnt vmcnt(1)
	v_pk_fma_f32 v[6:7], v[152:153], v[50:51], v[6:7] op_sel_hi:[1,0,1]
	v_pk_fma_f32 v[8:9], v[154:155], v[50:51], v[8:9] op_sel_hi:[1,0,1]
	v_pk_fma_f32 v[10:11], v[152:153], v[58:59], v[10:11] op_sel_hi:[1,0,1]
	v_pk_fma_f32 v[12:13], v[154:155], v[58:59], v[12:13] op_sel_hi:[1,0,1]
	v_pk_fma_f32 v[14:15], v[152:153], v[66:67], v[14:15] op_sel_hi:[1,0,1]
	v_pk_fma_f32 v[16:17], v[154:155], v[66:67], v[16:17] op_sel_hi:[1,0,1]
	v_pk_fma_f32 v[18:19], v[152:153], v[74:75], v[18:19] op_sel_hi:[1,0,1]
	v_pk_fma_f32 v[20:21], v[154:155], v[74:75], v[20:21] op_sel_hi:[1,0,1]
	v_pk_fma_f32 v[2:3], v[152:153], v[82:83], v[2:3] op_sel_hi:[1,0,1]
	v_pk_fma_f32 v[4:5], v[154:155], v[82:83], v[4:5] op_sel_hi:[1,0,1]
	s_waitcnt vmcnt(0)
	v_pk_fma_f32 v[6:7], v[156:157], v[50:51], v[6:7] op_sel:[0,1,0]
	v_pk_fma_f32 v[8:9], v[158:159], v[50:51], v[8:9] op_sel:[0,1,0]
	v_pk_fma_f32 v[10:11], v[156:157], v[58:59], v[10:11] op_sel:[0,1,0]
	v_pk_fma_f32 v[12:13], v[158:159], v[58:59], v[12:13] op_sel:[0,1,0]
	v_pk_fma_f32 v[14:15], v[156:157], v[66:67], v[14:15] op_sel:[0,1,0]
	v_pk_fma_f32 v[16:17], v[158:159], v[66:67], v[16:17] op_sel:[0,1,0]
	v_pk_fma_f32 v[18:19], v[156:157], v[74:75], v[18:19] op_sel:[0,1,0]
	v_pk_fma_f32 v[20:21], v[158:159], v[74:75], v[20:21] op_sel:[0,1,0]
	v_pk_fma_f32 v[2:3], v[156:157], v[82:83], v[2:3] op_sel:[0,1,0]
	v_pk_fma_f32 v[4:5], v[158:159], v[82:83], v[4:5] op_sel:[0,1,0]
	ds_write_b128 v23, v[6:9] offset:20480
	ds_write_b128 v23, v[10:13] offset:21504
	ds_write_b128 v23, v[14:17] offset:22528
	ds_write_b128 v23, v[18:21] offset:23552
	ds_write_b128 v23, v[2:5] offset:24576
	s_waitcnt lgkmcnt(0)
	s_barrier
	s_and_saveexec_b64 s[50:51], s[4:5]
	s_cbranch_execz .LBB0_7
	s_mul_i32 s65, s52, 0x9000
	s_mul_hi_i32 s53, s52, 0x9000
	s_add_u32 s65, s34, s65
	s_addc_u32 s53, s35, s53
	s_add_u32 s66, s65, s48
	s_addc_u32 s67, s53, s49
	v_mov_b32_e32 v33, v25
	s_mul_hi_i32 s53, s52, 5
	s_mul_i32 s52, s52, 5
	v_lshl_add_u64 v[2:3], s[66:67], 0, v[32:33]
	v_lshl_add_u64 v[4:5], v[26:27], 0, s[48:49]
	s_mov_b64 s[48:49], 0
	v_mov_b32_e32 v6, v22
